# baseline (speedup 1.0000x reference)
; __device__ __forceinline__ float sigmoidf_(float x) { return __builtin_amdgcn_rcpf(1.f + __expf(-x)); }
; __device__ __forceinline__ u16 f2bf(float f) {
;   u32 u = __float_as_uint(f);
;   u += 0x7fffu + ((u >> 16) & 1u);
;   return (u16)(u >> 16);
; }
; __device__ __forceinline__ float bf2f(u16 h) { return __uint_as_float(((u32)h) << 16); }
; __device__ __forceinline__ float bflo(u32 w) { return __uint_as_float(w << 16); }
; __device__ __forceinline__ float bfhi(u32 w) { return __uint_as_float(w & 0xffff0000u); }
; __device__ __forceinline__ u32 pack2(float a, float b) { return (u32)f2bf(a) | ((u32)f2bf(b) << 16); }
; __device__ __forceinline__ void gemm_tile(const GemmArgs& ga, int wgid, int next_wgid, bool prefetched, u16* shm, unsigned char* ws, int wv_) {
;     ...
;   if (epi == EPI_SWIGLU) {
;     const int oc = pn * HALF + (wc * 16 + fr) * 2;
;     float sc[2][4][4];
;     _Pragma("unroll") for (int ai = 0; ai < 2; ++ai)
;       _Pragma("unroll") for (int m = 0; m < 4; ++m)
;         _Pragma("unroll") for (int j = 0; j < 4; ++j) sc[ai][m][j] = e_ss[rbase + ai * HALF + m * 16 + j];
;     _Pragma("unroll") for (int ai = 0; ai < 2; ++ai)
;       _Pragma("unroll") for (int m = 0; m < 4; ++m)
;         _Pragma("unroll") for (int j = 0; j < 4; ++j) {
;           int row = rbase + ai * HALF + m * 16 + j;
;           float s = rsqrtf(sc[ai][m][j] * (1.f / D_) + 1e-6f);
;           float h2[2];
;           _Pragma("unroll") for (int n = 0; n < 2; ++n) {
;             float a1 = acc[ai][0][m][n][j] * s, a3 = acc[ai][1][m][n][j] * s;
;             h2[n] = a1 * sigmoidf_(a1) * a3;
;           }
;           *(u32*)(e_outb + (size_t)row * F_ + oc) = pack2(h2[0], h2[1]);
;         }
.LBB0_1263:
	s_lshl_b32 s2, s87, 7
	v_ashrrev_i32_e32 v169, 31, v168
	v_lshl_or_b32 v0, v187, 1, s2
	v_lshl_add_u64 v[132:133], v[168:169], 2, s[68:69]
	v_ashrrev_i32_e32 v1, 31, v0
	v_lshl_add_u64 v[128:129], v[0:1], 1, s[90:91]
	global_load_dwordx4 v[0:3], v[132:133], off
	s_movk_i32 s8, 0x2c00
	v_mad_i64_i32 v[134:135], s[2:3], v168, s8, v[128:129]
	s_mov_b32 s2, 0x358637bd
	s_nop 0
	v_mov_b64_e32 v[130:131], s[2:3]
	s_mov_b32 s12, 0x3a000000
	v_or_b32_e32 v8, 1, v168
	v_or_b32_e32 v9, 2, v168
	v_or_b32_e32 v10, 3, v168
	v_or_b32_e32 v11, 16, v168
	v_or_b32_e32 v162, 17, v168
	v_or_b32_e32 v161, 18, v168
	v_or_b32_e32 v160, 19, v168
	v_or_b32_e32 v159, 32, v168
	v_or_b32_e32 v158, 33, v168
	v_or_b32_e32 v157, 34, v168
	v_or_b32_e32 v156, 35, v168
	v_or_b32_e32 v155, 48, v168
	v_or_b32_e32 v154, 49, v168
	v_or_b32_e32 v153, 50, v168
	v_or_b32_e32 v152, 51, v168
	v_add_u32_e32 v151, 0x80, v168
	v_add_u32_e32 v150, 0x81, v168
	v_add_u32_e32 v149, 0x82, v168
	v_add_u32_e32 v148, 0x83, v168
	v_add_u32_e32 v147, 0x90, v168
	v_add_u32_e32 v146, 0x91, v168
	v_add_u32_e32 v145, 0x92, v168
	v_add_u32_e32 v144, 0x93, v168
	v_add_u32_e32 v143, 0xa0, v168
	v_add_u32_e32 v142, 0xa1, v168
	v_add_u32_e32 v141, 0xa2, v168
	v_add_u32_e32 v140, 0xa3, v168
	v_add_u32_e32 v139, 0xb0, v168
	v_add_u32_e32 v138, 0xb1, v168
	v_add_u32_e32 v137, 0xb2, v168
	v_add_u32_e32 v136, 0xb3, v168
	s_waitcnt vmcnt(0)
	v_pk_fma_f32 v[0:1], v[0:1], s[12:13], v[130:131] op_sel_hi:[1,0,0]
	s_nop 0
	v_pk_fma_f32 v[2:3], v[2:3], s[12:13], v[130:131] op_sel_hi:[1,0,0]
	v_rsq_f32_e32 v0, v0
	s_nop 0
	v_mul_f32_e32 v16, v116, v0
	v_mul_f32_e32 v18, 0xbfb8aa3b, v16
	v_exp_f32_e32 v18, v18
	v_mul_f32_e32 v17, v124, v0
	v_add_f32_e32 v18, 1.0, v18
	v_rcp_f32_e32 v18, v18
	s_nop 0
	v_mul_f32_e32 v16, v16, v18
	v_mul_f32_e32 v16, v17, v16
	v_mul_f32_e32 v17, v112, v0
	v_mul_f32_e32 v18, 0xbfb8aa3b, v17
	v_exp_f32_e32 v18, v18
	v_mul_f32_e32 v0, v120, v0
	v_add_f32_e32 v18, 1.0, v18
	v_rcp_f32_e32 v18, v18
	s_nop 0
	v_mul_f32_e32 v17, v17, v18
	v_mul_f32_e32 v0, v0, v17
	v_cvt_pk_bf16_f32 v0, v16, v0
	global_store_dword v[134:135], v0, off
	v_rsq_f32_e32 v0, v1
	s_nop 0
	v_mul_f32_e32 v1, v117, v0
	v_mul_f32_e32 v17, 0xbfb8aa3b, v1
	v_exp_f32_e32 v17, v17
	v_mul_f32_e32 v16, v125, v0
	v_mad_i64_i32 v[116:117], s[2:3], v11, s8, v[128:129]
	v_add_f32_e32 v17, 1.0, v17
	v_rcp_f32_e32 v17, v17
	s_nop 0
	v_mul_f32_e32 v1, v1, v17
	v_mul_f32_e32 v1, v16, v1
	v_mul_f32_e32 v16, v113, v0
	v_mul_f32_e32 v17, 0xbfb8aa3b, v16
	v_exp_f32_e32 v17, v17
	v_mul_f32_e32 v0, v121, v0
	v_add_f32_e32 v17, 1.0, v17
	v_rcp_f32_e32 v17, v17
	s_nop 0
	v_mul_f32_e32 v16, v16, v17
	v_mul_f32_e32 v0, v0, v16
	v_cvt_pk_bf16_f32 v16, v1, v0
	v_mad_i64_i32 v[0:1], s[2:3], v8, s8, v[128:129]
	v_rsq_f32_e32 v2, v2
	global_store_dword v[0:1], v16, off
	v_mad_i64_i32 v[0:1], s[2:3], v9, s8, v[128:129]
	v_mul_f32_e32 v8, v118, v2
	v_mul_f32_e32 v16, 0xbfb8aa3b, v8
	v_exp_f32_e32 v16, v16
	v_mul_f32_e32 v9, v126, v2
	v_add_f32_e32 v16, 1.0, v16
	v_rcp_f32_e32 v16, v16
	s_nop 0
	v_mul_f32_e32 v8, v8, v16
	v_mul_f32_e32 v8, v9, v8
	v_mul_f32_e32 v9, v114, v2
	v_mul_f32_e32 v16, 0xbfb8aa3b, v9
	v_exp_f32_e32 v16, v16
	v_mul_f32_e32 v2, v122, v2
	v_add_f32_e32 v16, 1.0, v16
	v_rcp_f32_e32 v16, v16
	s_nop 0
	v_mul_f32_e32 v9, v9, v16
	v_mul_f32_e32 v2, v2, v9
	v_cvt_pk_bf16_f32 v2, v8, v2
	global_store_dword v[0:1], v2, off
	v_rsq_f32_e32 v0, v3
	global_load_dwordx4 v[16:19], v[132:133], off offset:704
	v_mul_f32_e32 v1, v119, v0
	v_mul_f32_e32 v3, 0xbfb8aa3b, v1
	v_exp_f32_e32 v3, v3
	v_mul_f32_e32 v2, v127, v0
	v_add_f32_e32 v3, 1.0, v3
	v_rcp_f32_e32 v3, v3
	s_nop 0
	v_mul_f32_e32 v1, v1, v3
	v_mul_f32_e32 v1, v2, v1
	v_mul_f32_e32 v2, v115, v0
	global_load_dwordx4 v[112:115], v[132:133], off offset:64
	v_mul_f32_e32 v3, 0xbfb8aa3b, v2
	v_exp_f32_e32 v3, v3
	v_mul_f32_e32 v0, v123, v0
	v_add_f32_e32 v3, 1.0, v3
	v_rcp_f32_e32 v3, v3
	s_nop 0
	v_mul_f32_e32 v2, v2, v3
	v_mul_f32_e32 v0, v0, v2
	v_cvt_pk_bf16_f32 v2, v1, v0
	v_mad_i64_i32 v[0:1], s[2:3], v10, s8, v[128:129]
	global_store_dword v[0:1], v2, off
	s_waitcnt vmcnt(0)
	v_pk_fma_f32 v[0:1], v[112:113], s[12:13], v[130:131] op_sel_hi:[1,0,0]
	s_nop 0
	s_nop 0
	v_rsq_f32_e32 v0, v0
	s_nop 0
	v_mul_f32_e32 v2, v100, v0
	v_mul_f32_e32 v8, 0xbfb8aa3b, v2
	v_exp_f32_e32 v8, v8
	v_mul_f32_e32 v3, v108, v0
	v_add_f32_e32 v8, 1.0, v8
	v_rcp_f32_e32 v8, v8
	s_nop 0
	v_mul_f32_e32 v2, v2, v8
	v_mul_f32_e32 v2, v3, v2
	v_mul_f32_e32 v3, v96, v0
	v_mul_f32_e32 v8, 0xbfb8aa3b, v3
	v_exp_f32_e32 v8, v8
	v_mul_f32_e32 v0, v104, v0
	v_add_f32_e32 v8, 1.0, v8
	v_rcp_f32_e32 v8, v8
	s_nop 0
	v_mul_f32_e32 v3, v3, v8
	v_mul_f32_e32 v0, v0, v3
	v_cvt_pk_bf16_f32 v0, v2, v0
	global_store_dword v[116:117], v0, off
	v_rsq_f32_e32 v0, v1
	s_nop 0
	v_mul_f32_e32 v1, v101, v0
	v_mul_f32_e32 v3, 0xbfb8aa3b, v1
	v_exp_f32_e32 v3, v3
	v_mul_f32_e32 v2, v109, v0
	v_add_f32_e32 v3, 1.0, v3
	v_rcp_f32_e32 v3, v3
	s_nop 0
	v_mul_f32_e32 v1, v1, v3
	v_mul_f32_e32 v1, v2, v1
	v_mul_f32_e32 v2, v97, v0
	v_mul_f32_e32 v3, 0xbfb8aa3b, v2
	v_exp_f32_e32 v3, v3
	v_mul_f32_e32 v0, v105, v0
	v_mad_i64_i32 v[96:97], s[2:3], v159, s8, v[128:129]
	v_add_f32_e32 v3, 1.0, v3
	v_rcp_f32_e32 v3, v3
	s_nop 0
	v_mul_f32_e32 v2, v2, v3
	v_mul_f32_e32 v0, v0, v2
	v_cvt_pk_bf16_f32 v2, v1, v0
	v_mad_i64_i32 v[0:1], s[2:3], v162, s8, v[128:129]
	global_store_dword v[0:1], v2, off
	v_pk_fma_f32 v[2:3], v[114:115], s[12:13], v[130:131] op_sel_hi:[1,0,0]
	v_mad_i64_i32 v[0:1], s[2:3], v161, s8, v[128:129]
	s_nop 0
	v_rsq_f32_e32 v2, v2
	s_nop 0
	v_mul_f32_e32 v8, v102, v2
	v_mul_f32_e32 v10, 0xbfb8aa3b, v8
	v_exp_f32_e32 v10, v10
	v_mul_f32_e32 v9, v110, v2
	v_add_f32_e32 v10, 1.0, v10
	v_rcp_f32_e32 v10, v10
	s_nop 0
	v_mul_f32_e32 v8, v8, v10
	v_mul_f32_e32 v8, v9, v8
	v_mul_f32_e32 v9, v98, v2
	v_mul_f32_e32 v10, 0xbfb8aa3b, v9
	v_exp_f32_e32 v10, v10
	v_mul_f32_e32 v2, v106, v2
	v_add_f32_e32 v10, 1.0, v10
	v_rcp_f32_e32 v10, v10
	s_nop 0
	v_mul_f32_e32 v9, v9, v10
	v_mul_f32_e32 v2, v2, v9
	v_cvt_pk_bf16_f32 v2, v8, v2
	global_store_dword v[0:1], v2, off
	v_rsq_f32_e32 v0, v3
	s_nop 0
	v_mul_f32_e32 v1, v103, v0
	v_mul_f32_e32 v3, 0xbfb8aa3b, v1
	v_exp_f32_e32 v3, v3
	v_mul_f32_e32 v2, v111, v0
	v_add_f32_e32 v3, 1.0, v3
	v_rcp_f32_e32 v3, v3
	s_nop 0
	v_mul_f32_e32 v1, v1, v3
	v_mul_f32_e32 v1, v2, v1
	v_mul_f32_e32 v2, v99, v0
	v_mul_f32_e32 v3, 0xbfb8aa3b, v2
	v_exp_f32_e32 v3, v3
	v_mul_f32_e32 v0, v107, v0
	v_add_f32_e32 v3, 1.0, v3
	v_rcp_f32_e32 v3, v3
	s_nop 0
	v_mul_f32_e32 v2, v2, v3
	v_mul_f32_e32 v0, v0, v2
	v_cvt_pk_bf16_f32 v2, v1, v0
	v_mad_i64_i32 v[0:1], s[2:3], v160, s8, v[128:129]
	global_store_dword v[0:1], v2, off
	global_load_dwordx4 v[0:3], v[132:133], off offset:128
	s_waitcnt vmcnt(0)
; __device__ __forceinline__ float sigmoidf_(float x) { return __builtin_amdgcn_rcpf(1.f + __expf(-x)); }
; __device__ __forceinline__ u16 f2bf(float f) {
;   u32 u = __float_as_uint(f);
;   u += 0x7fffu + ((u >> 16) & 1u);
;   return (u16)(u >> 16);
; }
; __device__ __forceinline__ float bf2f(u16 h) { return __uint_as_float(((u32)h) << 16); }
; __device__ __forceinline__ float bflo(u32 w) { return __uint_as_float(w << 16); }
; __device__ __forceinline__ float bfhi(u32 w) { return __uint_as_float(w & 0xffff0000u); }
; __device__ __forceinline__ u32 pack2(float a, float b) { return (u32)f2bf(a) | ((u32)f2bf(b) << 16); }
; __device__ __forceinline__ void gemm_tile(const GemmArgs& ga, int wgid, int next_wgid, bool prefetched, u16* shm, unsigned char* ws, int wv_) {
;     ...
;   if (epi == EPI_SWIGLU) {
;     const int oc = pn * HALF + (wc * 16 + fr) * 2;
;     float sc[2][4][4];
;     _Pragma("unroll") for (int ai = 0; ai < 2; ++ai)
;       _Pragma("unroll") for (int m = 0; m < 4; ++m)
;         _Pragma("unroll") for (int j = 0; j < 4; ++j) sc[ai][m][j] = e_ss[rbase + ai * HALF + m * 16 + j];
;     _Pragma("unroll") for (int ai = 0; ai < 2; ++ai)
;       _Pragma("unroll") for (int m = 0; m < 4; ++m)
;         _Pragma("unroll") for (int j = 0; j < 4; ++j) {
;           int row = rbase + ai * HALF + m * 16 + j;
;           float s = rsqrtf(sc[ai][m][j] * (1.f / D_) + 1e-6f);
;           float h2[2];
;           _Pragma("unroll") for (int n = 0; n < 2; ++n) {
;             float a1 = acc[ai][0][m][n][j] * s, a3 = acc[ai][1][m][n][j] * s;
;             h2[n] = a1 * sigmoidf_(a1) * a3;
;           }
;           *(u32*)(e_outb + (size_t)row * F_ + oc) = pack2(h2[0], h2[1]);
;         }
	v_pk_fma_f32 v[0:1], v[0:1], s[12:13], v[130:131] op_sel_hi:[1,0,0]
	s_nop 0
	v_pk_fma_f32 v[2:3], v[2:3], s[12:13], v[130:131] op_sel_hi:[1,0,0]
	v_rsq_f32_e32 v0, v0
	s_nop 0
	v_mul_f32_e32 v8, v84, v0
	v_mul_f32_e32 v10, 0xbfb8aa3b, v8
	v_exp_f32_e32 v10, v10
	v_mul_f32_e32 v9, v92, v0
	v_add_f32_e32 v10, 1.0, v10
	v_rcp_f32_e32 v10, v10
	s_nop 0
	v_mul_f32_e32 v8, v8, v10
	v_mul_f32_e32 v8, v9, v8
	v_mul_f32_e32 v9, v80, v0
	v_mul_f32_e32 v10, 0xbfb8aa3b, v9
	v_exp_f32_e32 v10, v10
	v_mul_f32_e32 v0, v88, v0
	v_add_f32_e32 v10, 1.0, v10
	v_rcp_f32_e32 v10, v10
	s_nop 0
	v_mul_f32_e32 v9, v9, v10
	v_mul_f32_e32 v0, v0, v9
	v_cvt_pk_bf16_f32 v0, v8, v0
	global_store_dword v[96:97], v0, off
	v_rsq_f32_e32 v0, v1
	s_nop 0
	v_mul_f32_e32 v1, v85, v0
	v_mul_f32_e32 v9, 0xbfb8aa3b, v1
	v_exp_f32_e32 v9, v9
	v_mul_f32_e32 v8, v93, v0
	v_mad_i64_i32 v[84:85], s[2:3], v155, s8, v[128:129]
	v_add_f32_e32 v9, 1.0, v9
	v_rcp_f32_e32 v9, v9
	s_nop 0
	v_mul_f32_e32 v1, v1, v9
	v_mul_f32_e32 v1, v8, v1
	v_mul_f32_e32 v8, v81, v0
	v_mul_f32_e32 v9, 0xbfb8aa3b, v8
	v_exp_f32_e32 v9, v9
	v_mul_f32_e32 v0, v89, v0
	v_add_f32_e32 v9, 1.0, v9
	v_rcp_f32_e32 v9, v9
	s_nop 0
	v_mul_f32_e32 v8, v8, v9
	v_mul_f32_e32 v0, v0, v8
	v_cvt_pk_bf16_f32 v8, v1, v0
	v_mad_i64_i32 v[0:1], s[2:3], v158, s8, v[128:129]
	global_store_dword v[0:1], v8, off
	v_rsq_f32_e32 v2, v2
	v_mad_i64_i32 v[0:1], s[2:3], v157, s8, v[128:129]
	v_mul_f32_e32 v8, v86, v2
	v_mul_f32_e32 v10, 0xbfb8aa3b, v8
	v_exp_f32_e32 v10, v10
	v_mul_f32_e32 v9, v94, v2
	v_add_f32_e32 v10, 1.0, v10
	v_rcp_f32_e32 v10, v10
	s_nop 0
	v_mul_f32_e32 v8, v8, v10
	v_mul_f32_e32 v8, v9, v8
	v_mul_f32_e32 v9, v82, v2
	v_mul_f32_e32 v10, 0xbfb8aa3b, v9
	v_exp_f32_e32 v10, v10
	v_mul_f32_e32 v2, v90, v2
	v_add_f32_e32 v10, 1.0, v10
	v_rcp_f32_e32 v10, v10
	s_nop 0
	v_mul_f32_e32 v9, v9, v10
	v_mul_f32_e32 v2, v2, v9
	v_cvt_pk_bf16_f32 v2, v8, v2
	global_store_dword v[0:1], v2, off
	v_rsq_f32_e32 v0, v3
	s_nop 0
	v_mul_f32_e32 v1, v87, v0
	v_mul_f32_e32 v3, 0xbfb8aa3b, v1
	v_exp_f32_e32 v3, v3
	v_mul_f32_e32 v2, v95, v0
	v_add_f32_e32 v3, 1.0, v3
	v_rcp_f32_e32 v3, v3
	s_nop 0
	v_mul_f32_e32 v1, v1, v3
	v_mul_f32_e32 v1, v2, v1
	v_mul_f32_e32 v2, v83, v0
	global_load_dwordx4 v[80:83], v[132:133], off offset:192
	v_mul_f32_e32 v3, 0xbfb8aa3b, v2
	v_exp_f32_e32 v3, v3
	v_mul_f32_e32 v0, v91, v0
	v_add_f32_e32 v3, 1.0, v3
	v_rcp_f32_e32 v3, v3
	s_nop 0
	v_mul_f32_e32 v2, v2, v3
	v_mul_f32_e32 v0, v0, v2
	v_cvt_pk_bf16_f32 v2, v1, v0
	v_mad_i64_i32 v[0:1], s[2:3], v156, s8, v[128:129]
	global_store_dword v[0:1], v2, off
	s_waitcnt vmcnt(0)
	v_pk_fma_f32 v[0:1], v[80:81], s[12:13], v[130:131] op_sel_hi:[1,0,0]
	s_nop 0
	s_nop 0
	v_rsq_f32_e32 v0, v0
	s_nop 0
	v_mul_f32_e32 v2, v68, v0
	v_mul_f32_e32 v8, 0xbfb8aa3b, v2
	v_exp_f32_e32 v8, v8
	v_mul_f32_e32 v3, v76, v0
	v_add_f32_e32 v8, 1.0, v8
	v_rcp_f32_e32 v8, v8
	s_nop 0
	v_mul_f32_e32 v2, v2, v8
	v_mul_f32_e32 v2, v3, v2
	v_mul_f32_e32 v3, v64, v0
	v_mul_f32_e32 v8, 0xbfb8aa3b, v3
	v_exp_f32_e32 v8, v8
	v_mul_f32_e32 v0, v72, v0
	v_add_f32_e32 v8, 1.0, v8
	v_rcp_f32_e32 v8, v8
	s_nop 0
	v_mul_f32_e32 v3, v3, v8
	v_mul_f32_e32 v0, v0, v3
	v_cvt_pk_bf16_f32 v0, v2, v0
	global_store_dword v[84:85], v0, off
	v_rsq_f32_e32 v0, v1
	s_nop 0
	v_mul_f32_e32 v1, v69, v0
	v_mul_f32_e32 v3, 0xbfb8aa3b, v1
	v_exp_f32_e32 v3, v3
	v_mul_f32_e32 v2, v77, v0
	v_add_f32_e32 v3, 1.0, v3
	v_rcp_f32_e32 v3, v3
	s_nop 0
	v_mul_f32_e32 v1, v1, v3
	v_mul_f32_e32 v1, v2, v1
	v_mul_f32_e32 v2, v65, v0
	v_mul_f32_e32 v3, 0xbfb8aa3b, v2
	v_exp_f32_e32 v3, v3
	v_mul_f32_e32 v0, v73, v0
	v_mad_i64_i32 v[64:65], s[2:3], v151, s8, v[128:129]
	v_add_f32_e32 v3, 1.0, v3
	v_rcp_f32_e32 v3, v3
	s_nop 0
	v_mul_f32_e32 v2, v2, v3
	v_mul_f32_e32 v0, v0, v2
	v_cvt_pk_bf16_f32 v2, v1, v0
	v_mad_i64_i32 v[0:1], s[2:3], v154, s8, v[128:129]
	global_store_dword v[0:1], v2, off
	v_pk_fma_f32 v[2:3], v[82:83], s[12:13], v[130:131] op_sel_hi:[1,0,0]
	v_mad_i64_i32 v[0:1], s[2:3], v153, s8, v[128:129]
	s_nop 0
	v_rsq_f32_e32 v2, v2
	s_nop 0
	v_mul_f32_e32 v8, v70, v2
	v_mul_f32_e32 v10, 0xbfb8aa3b, v8
	v_exp_f32_e32 v10, v10
	v_mul_f32_e32 v9, v78, v2
	v_add_f32_e32 v10, 1.0, v10
	v_rcp_f32_e32 v10, v10
	s_nop 0
	v_mul_f32_e32 v8, v8, v10
	v_mul_f32_e32 v8, v9, v8
	v_mul_f32_e32 v9, v66, v2
	v_mul_f32_e32 v10, 0xbfb8aa3b, v9
	v_exp_f32_e32 v10, v10
	v_mul_f32_e32 v2, v74, v2
	v_add_f32_e32 v10, 1.0, v10
	v_rcp_f32_e32 v10, v10
	s_nop 0
	v_mul_f32_e32 v9, v9, v10
	v_mul_f32_e32 v2, v2, v9
	v_cvt_pk_bf16_f32 v2, v8, v2
	global_store_dword v[0:1], v2, off
	v_rsq_f32_e32 v0, v3
	s_nop 0
	v_mul_f32_e32 v1, v71, v0
	v_mul_f32_e32 v3, 0xbfb8aa3b, v1
	v_exp_f32_e32 v3, v3
	v_mul_f32_e32 v2, v79, v0
	v_add_f32_e32 v3, 1.0, v3
	v_rcp_f32_e32 v3, v3
	s_nop 0
	v_mul_f32_e32 v1, v1, v3
	v_mul_f32_e32 v1, v2, v1
	v_mul_f32_e32 v2, v67, v0
	v_mul_f32_e32 v3, 0xbfb8aa3b, v2
	v_exp_f32_e32 v3, v3
	v_mul_f32_e32 v0, v75, v0
	v_add_f32_e32 v3, 1.0, v3
	v_rcp_f32_e32 v3, v3
	s_nop 0
	v_mul_f32_e32 v2, v2, v3
	v_mul_f32_e32 v0, v0, v2
	v_cvt_pk_bf16_f32 v2, v1, v0
	v_mad_i64_i32 v[0:1], s[2:3], v152, s8, v[128:129]
	global_store_dword v[0:1], v2, off
	global_load_dwordx4 v[0:3], v[132:133], off offset:512
	s_waitcnt vmcnt(0)
; __device__ __forceinline__ float sigmoidf_(float x) { return __builtin_amdgcn_rcpf(1.f + __expf(-x)); }
; __device__ __forceinline__ u16 f2bf(float f) {
;   u32 u = __float_as_uint(f);
;   u += 0x7fffu + ((u >> 16) & 1u);
;   return (u16)(u >> 16);
; }
; __device__ __forceinline__ float bf2f(u16 h) { return __uint_as_float(((u32)h) << 16); }
; __device__ __forceinline__ float bflo(u32 w) { return __uint_as_float(w << 16); }
; __device__ __forceinline__ float bfhi(u32 w) { return __uint_as_float(w & 0xffff0000u); }
; __device__ __forceinline__ u32 pack2(float a, float b) { return (u32)f2bf(a) | ((u32)f2bf(b) << 16); }
; __device__ __forceinline__ void gemm_tile(const GemmArgs& ga, int wgid, int next_wgid, bool prefetched, u16* shm, unsigned char* ws, int wv_) {
;     ...
;   if (epi == EPI_SWIGLU) {
;     const int oc = pn * HALF + (wc * 16 + fr) * 2;
;     float sc[2][4][4];
;     _Pragma("unroll") for (int ai = 0; ai < 2; ++ai)
;       _Pragma("unroll") for (int m = 0; m < 4; ++m)
;         _Pragma("unroll") for (int j = 0; j < 4; ++j) sc[ai][m][j] = e_ss[rbase + ai * HALF + m * 16 + j];
;     _Pragma("unroll") for (int ai = 0; ai < 2; ++ai)
;       _Pragma("unroll") for (int m = 0; m < 4; ++m)
;         _Pragma("unroll") for (int j = 0; j < 4; ++j) {
;           int row = rbase + ai * HALF + m * 16 + j;
;           float s = rsqrtf(sc[ai][m][j] * (1.f / D_) + 1e-6f);
;           float h2[2];
;           _Pragma("unroll") for (int n = 0; n < 2; ++n) {
;             float a1 = acc[ai][0][m][n][j] * s, a3 = acc[ai][1][m][n][j] * s;
;             h2[n] = a1 * sigmoidf_(a1) * a3;
;           }
;           *(u32*)(e_outb + (size_t)row * F_ + oc) = pack2(h2[0], h2[1]);
;         }
	v_pk_fma_f32 v[0:1], v[0:1], s[12:13], v[130:131] op_sel_hi:[1,0,0]
	s_nop 0
	v_pk_fma_f32 v[2:3], v[2:3], s[12:13], v[130:131] op_sel_hi:[1,0,0]
	v_rsq_f32_e32 v0, v0
	s_nop 0
	v_mul_f32_e32 v8, v52, v0
	v_mul_f32_e32 v10, 0xbfb8aa3b, v8
	v_exp_f32_e32 v10, v10
	v_mul_f32_e32 v9, v60, v0
	v_add_f32_e32 v10, 1.0, v10
	v_rcp_f32_e32 v10, v10
	s_nop 0
	v_mul_f32_e32 v8, v8, v10
	v_mul_f32_e32 v8, v9, v8
	v_mul_f32_e32 v9, v48, v0
	v_mul_f32_e32 v10, 0xbfb8aa3b, v9
	v_exp_f32_e32 v10, v10
	v_mul_f32_e32 v0, v56, v0
	v_add_f32_e32 v10, 1.0, v10
	v_rcp_f32_e32 v10, v10
	s_nop 0
	v_mul_f32_e32 v9, v9, v10
	v_mul_f32_e32 v0, v0, v9
	v_cvt_pk_bf16_f32 v0, v8, v0
	global_store_dword v[64:65], v0, off
	v_rsq_f32_e32 v0, v1
	s_nop 0
	v_mul_f32_e32 v1, v53, v0
	v_mul_f32_e32 v9, 0xbfb8aa3b, v1
	v_exp_f32_e32 v9, v9
	v_mul_f32_e32 v8, v61, v0
	v_mad_i64_i32 v[52:53], s[2:3], v147, s8, v[128:129]
	v_add_f32_e32 v9, 1.0, v9
	v_rcp_f32_e32 v9, v9
	s_nop 0
	v_mul_f32_e32 v1, v1, v9
	v_mul_f32_e32 v1, v8, v1
	v_mul_f32_e32 v8, v49, v0
	v_mul_f32_e32 v9, 0xbfb8aa3b, v8
	v_exp_f32_e32 v9, v9
	v_mul_f32_e32 v0, v57, v0
	v_add_f32_e32 v9, 1.0, v9
	v_rcp_f32_e32 v9, v9
	s_nop 0
	v_mul_f32_e32 v8, v8, v9
	v_mul_f32_e32 v0, v0, v8
	v_cvt_pk_bf16_f32 v8, v1, v0
	v_mad_i64_i32 v[0:1], s[2:3], v150, s8, v[128:129]
	global_store_dword v[0:1], v8, off
	v_rsq_f32_e32 v2, v2
	v_mad_i64_i32 v[0:1], s[2:3], v149, s8, v[128:129]
	v_mul_f32_e32 v8, v54, v2
	v_mul_f32_e32 v10, 0xbfb8aa3b, v8
	v_exp_f32_e32 v10, v10
	v_mul_f32_e32 v9, v62, v2
	v_add_f32_e32 v10, 1.0, v10
	v_rcp_f32_e32 v10, v10
	s_nop 0
	v_mul_f32_e32 v8, v8, v10
	v_mul_f32_e32 v8, v9, v8
	v_mul_f32_e32 v9, v50, v2
	v_mul_f32_e32 v10, 0xbfb8aa3b, v9
	v_exp_f32_e32 v10, v10
	v_mul_f32_e32 v2, v58, v2
	v_add_f32_e32 v10, 1.0, v10
	v_rcp_f32_e32 v10, v10
	s_nop 0
	v_mul_f32_e32 v9, v9, v10
	v_mul_f32_e32 v2, v2, v9
	v_cvt_pk_bf16_f32 v2, v8, v2
	global_store_dword v[0:1], v2, off
	v_rsq_f32_e32 v0, v3
	s_nop 0
	v_mul_f32_e32 v1, v55, v0
	v_mul_f32_e32 v3, 0xbfb8aa3b, v1
	v_exp_f32_e32 v3, v3
	v_mul_f32_e32 v2, v63, v0
	v_add_f32_e32 v3, 1.0, v3
	v_rcp_f32_e32 v3, v3
	s_nop 0
	v_mul_f32_e32 v1, v1, v3
	v_mul_f32_e32 v1, v2, v1
	v_mul_f32_e32 v2, v51, v0
	global_load_dwordx4 v[48:51], v[132:133], off offset:576
	v_mul_f32_e32 v3, 0xbfb8aa3b, v2
	v_exp_f32_e32 v3, v3
	v_mul_f32_e32 v0, v59, v0
	v_add_f32_e32 v3, 1.0, v3
	v_rcp_f32_e32 v3, v3
	s_nop 0
	v_mul_f32_e32 v2, v2, v3
	v_mul_f32_e32 v0, v0, v2
	v_cvt_pk_bf16_f32 v2, v1, v0
	v_mad_i64_i32 v[0:1], s[2:3], v148, s8, v[128:129]
	global_store_dword v[0:1], v2, off
	s_waitcnt vmcnt(0)
	v_pk_fma_f32 v[0:1], v[48:49], s[12:13], v[130:131] op_sel_hi:[1,0,0]
	s_nop 0
	s_nop 0
	v_rsq_f32_e32 v0, v0
	s_nop 0
	v_mul_f32_e32 v2, v36, v0
	v_mul_f32_e32 v8, 0xbfb8aa3b, v2
	v_exp_f32_e32 v8, v8
	v_mul_f32_e32 v3, v44, v0
	v_add_f32_e32 v8, 1.0, v8
	v_rcp_f32_e32 v8, v8
	s_nop 0
	v_mul_f32_e32 v2, v2, v8
	v_mul_f32_e32 v2, v3, v2
	v_mul_f32_e32 v3, v32, v0
	v_mul_f32_e32 v8, 0xbfb8aa3b, v3
	v_exp_f32_e32 v8, v8
	v_mul_f32_e32 v0, v40, v0
	v_add_f32_e32 v8, 1.0, v8
	v_rcp_f32_e32 v8, v8
	s_nop 0
	v_mul_f32_e32 v3, v3, v8
	v_mul_f32_e32 v0, v0, v3
	v_cvt_pk_bf16_f32 v0, v2, v0
	global_store_dword v[52:53], v0, off
	v_rsq_f32_e32 v0, v1
	s_nop 0
	v_mul_f32_e32 v1, v37, v0
	v_mul_f32_e32 v3, 0xbfb8aa3b, v1
	v_exp_f32_e32 v3, v3
	v_mul_f32_e32 v2, v45, v0
	v_add_f32_e32 v3, 1.0, v3
	v_rcp_f32_e32 v3, v3
	s_nop 0
	v_mul_f32_e32 v1, v1, v3
	v_mul_f32_e32 v1, v2, v1
	v_mul_f32_e32 v2, v33, v0
	v_mul_f32_e32 v3, 0xbfb8aa3b, v2
	v_exp_f32_e32 v3, v3
	v_mul_f32_e32 v0, v41, v0
	v_mad_i64_i32 v[32:33], s[2:3], v143, s8, v[128:129]
	v_add_f32_e32 v3, 1.0, v3
	v_rcp_f32_e32 v3, v3
	s_nop 0
	v_mul_f32_e32 v2, v2, v3
	v_mul_f32_e32 v0, v0, v2
	v_cvt_pk_bf16_f32 v2, v1, v0
	v_mad_i64_i32 v[0:1], s[2:3], v146, s8, v[128:129]
	global_store_dword v[0:1], v2, off
	v_pk_fma_f32 v[2:3], v[50:51], s[12:13], v[130:131] op_sel_hi:[1,0,0]
	v_mad_i64_i32 v[0:1], s[2:3], v145, s8, v[128:129]
	s_nop 0
	v_rsq_f32_e32 v2, v2
	s_nop 0
	v_mul_f32_e32 v8, v38, v2
	v_mul_f32_e32 v10, 0xbfb8aa3b, v8
	v_exp_f32_e32 v10, v10
	v_mul_f32_e32 v9, v46, v2
	v_add_f32_e32 v10, 1.0, v10
	v_rcp_f32_e32 v10, v10
	s_nop 0
	v_mul_f32_e32 v8, v8, v10
	v_mul_f32_e32 v8, v9, v8
	v_mul_f32_e32 v9, v34, v2
	v_mul_f32_e32 v10, 0xbfb8aa3b, v9
	v_exp_f32_e32 v10, v10
	v_mul_f32_e32 v2, v42, v2
	v_add_f32_e32 v10, 1.0, v10
	v_rcp_f32_e32 v10, v10
	s_nop 0
	v_mul_f32_e32 v9, v9, v10
	v_mul_f32_e32 v2, v2, v9
	v_cvt_pk_bf16_f32 v2, v8, v2
	global_store_dword v[0:1], v2, off
	v_rsq_f32_e32 v0, v3
	s_nop 0
	v_mul_f32_e32 v1, v39, v0
	v_mul_f32_e32 v3, 0xbfb8aa3b, v1
	v_exp_f32_e32 v3, v3
	v_mul_f32_e32 v2, v47, v0
	v_add_f32_e32 v3, 1.0, v3
	v_rcp_f32_e32 v3, v3
	s_nop 0
	v_mul_f32_e32 v1, v1, v3
	v_mul_f32_e32 v1, v2, v1
	v_mul_f32_e32 v2, v35, v0
	v_mul_f32_e32 v3, 0xbfb8aa3b, v2
	v_exp_f32_e32 v3, v3
	v_mul_f32_e32 v0, v43, v0
	v_add_f32_e32 v3, 1.0, v3
	v_rcp_f32_e32 v3, v3
	s_nop 0
	v_mul_f32_e32 v2, v2, v3
	v_mul_f32_e32 v0, v0, v2
	v_cvt_pk_bf16_f32 v2, v1, v0
	v_mad_i64_i32 v[0:1], s[2:3], v144, s8, v[128:129]
	global_store_dword v[0:1], v2, off
	global_load_dwordx4 v[0:3], v[132:133], off offset:640
	s_waitcnt vmcnt(0)
; __device__ __forceinline__ float sigmoidf_(float x) { return __builtin_amdgcn_rcpf(1.f + __expf(-x)); }
; __device__ __forceinline__ u16 f2bf(float f) {
;   u32 u = __float_as_uint(f);
;   u += 0x7fffu + ((u >> 16) & 1u);
;   return (u16)(u >> 16);
; }
; __device__ __forceinline__ float bf2f(u16 h) { return __uint_as_float(((u32)h) << 16); }
; __device__ __forceinline__ float bflo(u32 w) { return __uint_as_float(w << 16); }
; __device__ __forceinline__ float bfhi(u32 w) { return __uint_as_float(w & 0xffff0000u); }
; __device__ __forceinline__ u32 pack2(float a, float b) { return (u32)f2bf(a) | ((u32)f2bf(b) << 16); }
; __device__ __forceinline__ void gemm_tile(const GemmArgs& ga, int wgid, int next_wgid, bool prefetched, u16* shm, unsigned char* ws, int wv_) {
;     ...
;   if (epi == EPI_SWIGLU) {
;     const int oc = pn * HALF + (wc * 16 + fr) * 2;
;     float sc[2][4][4];
;     _Pragma("unroll") for (int ai = 0; ai < 2; ++ai)
;       _Pragma("unroll") for (int m = 0; m < 4; ++m)
;         _Pragma("unroll") for (int j = 0; j < 4; ++j) sc[ai][m][j] = e_ss[rbase + ai * HALF + m * 16 + j];
;     _Pragma("unroll") for (int ai = 0; ai < 2; ++ai)
;       _Pragma("unroll") for (int m = 0; m < 4; ++m)
;         _Pragma("unroll") for (int j = 0; j < 4; ++j) {
;           int row = rbase + ai * HALF + m * 16 + j;
;           float s = rsqrtf(sc[ai][m][j] * (1.f / D_) + 1e-6f);
;           float h2[2];
;           _Pragma("unroll") for (int n = 0; n < 2; ++n) {
;             float a1 = acc[ai][0][m][n][j] * s, a3 = acc[ai][1][m][n][j] * s;
;             h2[n] = a1 * sigmoidf_(a1) * a3;
;           }
;           *(u32*)(e_outb + (size_t)row * F_ + oc) = pack2(h2[0], h2[1]);
;         }
	v_pk_fma_f32 v[0:1], v[0:1], s[12:13], v[130:131] op_sel_hi:[1,0,0]
	s_nop 0
	v_pk_fma_f32 v[2:3], v[2:3], s[12:13], v[130:131] op_sel_hi:[1,0,0]
	v_rsq_f32_e32 v0, v0
	s_nop 0
	v_mul_f32_e32 v8, v20, v0
	v_mul_f32_e32 v10, 0xbfb8aa3b, v8
	v_exp_f32_e32 v10, v10
	v_mul_f32_e32 v9, v244, v0
	v_add_f32_e32 v10, 1.0, v10
	v_rcp_f32_e32 v10, v10
	s_nop 0
	v_mul_f32_e32 v8, v8, v10
	v_mul_f32_e32 v8, v9, v8
	v_mul_f32_e32 v9, v240, v0
	v_mul_f32_e32 v10, 0xbfb8aa3b, v9
	v_exp_f32_e32 v10, v10
	v_mul_f32_e32 v0, v24, v0
	v_add_f32_e32 v10, 1.0, v10
	v_rcp_f32_e32 v10, v10
	s_nop 0
	v_mul_f32_e32 v9, v9, v10
	v_mul_f32_e32 v0, v0, v9
	v_cvt_pk_bf16_f32 v0, v8, v0
	global_store_dword v[32:33], v0, off
	v_rsq_f32_e32 v0, v1
	s_nop 0
	v_mul_f32_e32 v1, v21, v0
	v_mul_f32_e32 v9, 0xbfb8aa3b, v1
	v_exp_f32_e32 v9, v9
	v_mul_f32_e32 v8, v245, v0
	v_mad_i64_i32 v[20:21], s[2:3], v139, s8, v[128:129]
	v_add_f32_e32 v9, 1.0, v9
	v_rcp_f32_e32 v9, v9
	s_nop 0
	v_mul_f32_e32 v1, v1, v9
	v_mul_f32_e32 v1, v8, v1
	v_mul_f32_e32 v8, v241, v0
	v_mul_f32_e32 v9, 0xbfb8aa3b, v8
	v_exp_f32_e32 v9, v9
	v_mul_f32_e32 v0, v25, v0
	v_add_f32_e32 v9, 1.0, v9
	v_rcp_f32_e32 v9, v9
	s_nop 0
	v_mul_f32_e32 v8, v8, v9
	v_mul_f32_e32 v0, v0, v8
	v_cvt_pk_bf16_f32 v8, v1, v0
	v_mad_i64_i32 v[0:1], s[2:3], v142, s8, v[128:129]
	global_store_dword v[0:1], v8, off
	v_rsq_f32_e32 v2, v2
	v_mad_i64_i32 v[0:1], s[2:3], v141, s8, v[128:129]
	v_mul_f32_e32 v8, v22, v2
	v_mul_f32_e32 v10, 0xbfb8aa3b, v8
	v_exp_f32_e32 v10, v10
	v_mul_f32_e32 v9, v246, v2
	v_add_f32_e32 v10, 1.0, v10
	v_rcp_f32_e32 v10, v10
	s_nop 0
	v_mul_f32_e32 v8, v8, v10
	v_mul_f32_e32 v8, v9, v8
	v_mul_f32_e32 v9, v242, v2
	v_mul_f32_e32 v10, 0xbfb8aa3b, v9
	v_exp_f32_e32 v10, v10
	v_mul_f32_e32 v2, v26, v2
	v_add_f32_e32 v10, 1.0, v10
	v_rcp_f32_e32 v10, v10
	s_nop 0
	v_mul_f32_e32 v9, v9, v10
	v_mul_f32_e32 v2, v2, v9
	v_cvt_pk_bf16_f32 v2, v8, v2
	global_store_dword v[0:1], v2, off
	v_rsq_f32_e32 v0, v3
	s_nop 0
	v_mul_f32_e32 v1, v23, v0
	v_mul_f32_e32 v3, 0xbfb8aa3b, v1
	v_exp_f32_e32 v3, v3
	v_mul_f32_e32 v2, v247, v0
	v_add_f32_e32 v3, 1.0, v3
	v_rcp_f32_e32 v3, v3
	s_nop 0
	v_mul_f32_e32 v1, v1, v3
	v_mul_f32_e32 v1, v2, v1
	v_mul_f32_e32 v2, v243, v0
	v_mul_f32_e32 v3, 0xbfb8aa3b, v2
	v_exp_f32_e32 v3, v3
	v_mul_f32_e32 v0, v27, v0
	v_add_f32_e32 v3, 1.0, v3
	v_rcp_f32_e32 v3, v3
	s_nop 0
	v_mul_f32_e32 v2, v2, v3
	v_mul_f32_e32 v0, v0, v2
	v_cvt_pk_bf16_f32 v2, v1, v0
	v_mad_i64_i32 v[0:1], s[2:3], v140, s8, v[128:129]
	global_store_dword v[0:1], v2, off
	v_pk_fma_f32 v[0:1], v[16:17], s[12:13], v[130:131] op_sel_hi:[1,0,0]
	s_nop 0
	s_nop 0
	v_rsq_f32_e32 v0, v0
	s_nop 0
	v_mul_f32_e32 v2, v204, v0
	v_mul_f32_e32 v8, 0xbfb8aa3b, v2
	v_exp_f32_e32 v8, v8
	v_mul_f32_e32 v3, v12, v0
	v_add_f32_e32 v8, 1.0, v8
	v_rcp_f32_e32 v8, v8
	s_nop 0
	v_mul_f32_e32 v2, v2, v8
	v_mul_f32_e32 v2, v3, v2
	v_mul_f32_e32 v3, v182, v0
	v_mul_f32_e32 v0, v4, v0
	v_mul_f32_e32 v4, 0xbfb8aa3b, v3
	v_exp_f32_e32 v4, v4
	s_nop 0
	v_add_f32_e32 v4, 1.0, v4
	v_rcp_f32_e32 v4, v4
	s_nop 0
	v_mul_f32_e32 v3, v3, v4
	v_mul_f32_e32 v0, v0, v3
	v_cvt_pk_bf16_f32 v0, v2, v0
	global_store_dword v[20:21], v0, off
	v_rsq_f32_e32 v0, v1
	s_nop 0
	v_mul_f32_e32 v1, v205, v0
	v_mul_f32_e32 v3, 0xbfb8aa3b, v1
	v_exp_f32_e32 v3, v3
	v_mul_f32_e32 v2, v13, v0
	v_add_f32_e32 v3, 1.0, v3
	v_rcp_f32_e32 v3, v3
	s_nop 0
	v_mul_f32_e32 v1, v1, v3
	v_mul_f32_e32 v1, v2, v1
	v_mul_f32_e32 v2, v183, v0
	v_mul_f32_e32 v3, 0xbfb8aa3b, v2
	v_exp_f32_e32 v3, v3
	v_mul_f32_e32 v0, v5, v0
	v_add_f32_e32 v3, 1.0, v3
	v_rcp_f32_e32 v3, v3
	s_nop 0
	v_mul_f32_e32 v2, v2, v3
	v_mul_f32_e32 v0, v0, v2
	v_cvt_pk_bf16_f32 v2, v1, v0
	v_mad_i64_i32 v[0:1], s[2:3], v138, s8, v[128:129]
	global_store_dword v[0:1], v2, off
	v_pk_fma_f32 v[2:3], v[18:19], s[12:13], v[130:131] op_sel_hi:[1,0,0]
	v_mad_i64_i32 v[0:1], s[2:3], v137, s8, v[128:129]
	s_nop 0
	v_rsq_f32_e32 v2, v2
	s_nop 0
	v_mul_f32_e32 v4, v206, v2
	v_mul_f32_e32 v8, 0xbfb8aa3b, v4
	v_exp_f32_e32 v8, v8
	v_mul_f32_e32 v5, v14, v2
	v_add_f32_e32 v8, 1.0, v8
	v_rcp_f32_e32 v8, v8
	s_nop 0
	v_mul_f32_e32 v4, v4, v8
	v_mul_f32_e32 v4, v5, v4
	v_mul_f32_e32 v5, v184, v2
	v_mul_f32_e32 v2, v6, v2
	v_mul_f32_e32 v6, 0xbfb8aa3b, v5
	v_exp_f32_e32 v6, v6
	s_nop 0
	v_add_f32_e32 v6, 1.0, v6
	v_rcp_f32_e32 v6, v6
	s_nop 0
	v_mul_f32_e32 v5, v5, v6
	v_mul_f32_e32 v2, v2, v5
	v_cvt_pk_bf16_f32 v2, v4, v2
	global_store_dword v[0:1], v2, off
	v_rsq_f32_e32 v0, v3
	s_nop 0
	v_mul_f32_e32 v1, v207, v0
	v_mul_f32_e32 v3, 0xbfb8aa3b, v1
	v_exp_f32_e32 v3, v3
	v_mul_f32_e32 v2, v15, v0
	v_add_f32_e32 v3, 1.0, v3
	v_rcp_f32_e32 v3, v3
	s_nop 0
	v_mul_f32_e32 v1, v1, v3
	v_mul_f32_e32 v1, v2, v1
	v_mul_f32_e32 v2, v185, v0
	v_mul_f32_e32 v3, 0xbfb8aa3b, v2
	v_exp_f32_e32 v3, v3
	v_mul_f32_e32 v0, v7, v0
	v_add_f32_e32 v3, 1.0, v3
	v_rcp_f32_e32 v3, v3
	s_nop 0
	v_mul_f32_e32 v2, v2, v3
	v_mul_f32_e32 v0, v0, v2
	v_bfe_u32 v2, v1, 16, 1
	v_add3_u32 v1, v1, v2, s48
	v_bfe_u32 v2, v0, 16, 1
	v_lshrrev_b32_e32 v1, 16, v1
	v_add3_u32 v0, v0, v2, s48
	v_and_or_b32 v2, v0, s97, v1
	v_mad_i64_i32 v[0:1], s[2:3], v136, s8, v[128:129]
	global_store_dword v[0:1], v2, off
	s_branch .LBB0_501
